# conv inner loop: straight-lined the 17 exec-masked halo-load blocks per layer (deleted s_cbranch_execz over VALU+load-only blocks)
# baseline (speedup 1.0000x reference)
; __device__ __forceinline__ void phase_conv(PRef p, int layer, int nseg) {
;     ...
;         for (int hx = 0; hx < 2; ++hx) { const int xb = x0 + 4 * hx;
;             u32x4 gc[3][6], vv[4];
; #pragma unroll
;             for (int ky = 0; ky < 3; ++ky)
; #pragma unroll
;                 for (int cx = 0; cx < 6; ++cx) { const int xx = xb - 1 + cx;
;                     gc[ky][cx] = (lv[ky] && xx >= 0 && xx < W) ? *(const u32x4*)(lp[ky] + (size_t)xx * NUP) : (u32x4){0u, 0u, 0u, 0u}; }
.LBB0_552:
	s_nop 0
	v_add_u32_e32 v80, s4, v220
	v_add_u32_e32 v92, -1, v80
	v_cmp_gt_u32_e32 vcc, s30, v92
	s_and_b64 s[4:5], s[52:53], vcc
	v_mov_b32_e32 v124, 0
	v_mov_b32_e32 v132, 0
	v_mov_b32_e32 v133, 0
	v_mov_b32_e32 v134, 0
	v_mov_b32_e32 v135, 0
	s_and_saveexec_b64 s[2:3], s[4:5]
	v_mad_u64_u32 v[82:83], s[4:5], v92, s28, v[168:169]
	global_load_dwordx4 v[132:135], v[82:83], off
.LBB0_554:
	s_or_b64 exec, exec, s[2:3]
	v_cmp_gt_u32_e64 s[2:3], s30, v80
	s_and_b64 s[6:7], s[52:53], s[2:3]
	v_mov_b32_e32 v125, 0
	v_mov_b32_e32 v126, 0
	v_mov_b32_e32 v127, 0
	s_and_saveexec_b64 s[4:5], s[6:7]
	v_mad_u64_u32 v[82:83], s[6:7], v80, s28, v[168:169]
	global_load_dwordx4 v[124:127], v[82:83], off
.LBB0_556:
	s_or_b64 exec, exec, s[4:5]
	v_add_u32_e32 v81, 1, v80
	v_cmp_gt_u32_e64 s[4:5], s30, v81
	s_and_b64 s[8:9], s[52:53], s[4:5]
	v_mov_b32_e32 v104, 0
	v_mov_b32_e32 v136, 0
	v_mov_b32_e32 v137, 0
	v_mov_b32_e32 v138, 0
	v_mov_b32_e32 v139, 0
	s_and_saveexec_b64 s[6:7], s[8:9]
	v_mad_u64_u32 v[82:83], s[8:9], v81, s28, v[168:169]
	global_load_dwordx4 v[136:139], v[82:83], off
.LBB0_558:
	s_or_b64 exec, exec, s[6:7]
	v_add_u32_e32 v82, 2, v80
	v_cmp_gt_u32_e64 s[6:7], s30, v82
	s_and_b64 s[10:11], s[52:53], s[6:7]
	v_mov_b32_e32 v105, 0
	v_mov_b32_e32 v106, 0
	v_mov_b32_e32 v107, 0
	s_and_saveexec_b64 s[8:9], s[10:11]
	v_mad_u64_u32 v[84:85], s[10:11], v82, s28, v[168:169]
	global_load_dwordx4 v[104:107], v[84:85], off
.LBB0_560:
	s_or_b64 exec, exec, s[8:9]
	v_add_u32_e32 v83, 3, v80
	v_cmp_gt_u32_e64 s[8:9], s30, v83
	s_and_b64 s[34:35], s[52:53], s[8:9]
	v_mov_b32_e32 v100, 0
	v_mov_b32_e32 v108, 0
	v_mov_b32_e32 v109, 0
	v_mov_b32_e32 v110, 0
	v_mov_b32_e32 v111, 0
	s_and_saveexec_b64 s[10:11], s[34:35]
	v_mad_u64_u32 v[84:85], s[34:35], v83, s28, v[168:169]
	global_load_dwordx4 v[108:111], v[84:85], off
.LBB0_562:
	s_or_b64 exec, exec, s[10:11]
	v_add_u32_e32 v120, 4, v80
	v_cmp_gt_u32_e64 s[10:11], s30, v120
	s_and_b64 s[34:35], s[52:53], s[10:11]
	v_mov_b32_e32 v101, 0
	v_mov_b32_e32 v102, 0
	v_mov_b32_e32 v103, 0
	s_and_saveexec_b64 s[58:59], s[34:35]
	v_mad_u64_u32 v[84:85], s[34:35], v120, s28, v[168:169]
	global_load_dwordx4 v[100:103], v[84:85], off
.LBB0_564:
	s_or_b64 exec, exec, s[58:59]
	v_mov_b32_e32 v152, 0
	v_mov_b32_e32 v148, 0
	v_mov_b32_e32 v149, 0
	v_mov_b32_e32 v150, 0
	v_mov_b32_e32 v151, 0
	s_and_saveexec_b64 s[58:59], vcc
	v_mad_u64_u32 v[84:85], s[34:35], v92, s28, v[170:171]
	global_load_dwordx4 v[148:151], v[84:85], off
.LBB0_566:
	s_or_b64 exec, exec, s[58:59]
	v_mov_b32_e32 v153, 0
	v_mov_b32_e32 v154, 0
	v_mov_b32_e32 v155, 0
	s_and_saveexec_b64 s[58:59], s[2:3]
	v_mad_u64_u32 v[84:85], s[34:35], v80, s28, v[170:171]
	global_load_dwordx4 v[152:155], v[84:85], off
.LBB0_568:
	s_or_b64 exec, exec, s[58:59]
	v_mov_b32_e32 v88, 0
	v_mov_b32_e32 v144, 0
	v_mov_b32_e32 v145, 0
	v_mov_b32_e32 v146, 0
	v_mov_b32_e32 v147, 0
	s_and_saveexec_b64 s[58:59], s[4:5]
	v_mad_u64_u32 v[84:85], s[34:35], v81, s28, v[170:171]
	global_load_dwordx4 v[144:147], v[84:85], off
.LBB0_570:
	s_or_b64 exec, exec, s[58:59]
	v_mov_b32_e32 v89, 0
	v_mov_b32_e32 v90, 0
	v_mov_b32_e32 v91, 0
	s_and_saveexec_b64 s[58:59], s[6:7]
	v_mad_u64_u32 v[84:85], s[34:35], v82, s28, v[170:171]
	global_load_dwordx4 v[88:91], v[84:85], off
.LBB0_572:
	s_or_b64 exec, exec, s[58:59]
	v_mov_b32_e32 v84, 0
	v_mov_b32_e32 v96, 0
	v_mov_b32_e32 v97, 0
	v_mov_b32_e32 v98, 0
	v_mov_b32_e32 v99, 0
	s_and_saveexec_b64 s[58:59], s[8:9]
	v_mad_u64_u32 v[86:87], s[34:35], v83, s28, v[170:171]
	global_load_dwordx4 v[96:99], v[86:87], off
.LBB0_574:
	s_or_b64 exec, exec, s[58:59]
	v_mov_b32_e32 v85, 0
	v_mov_b32_e32 v86, 0
	v_mov_b32_e32 v87, 0
	s_and_saveexec_b64 s[58:59], s[10:11]
	v_mad_u64_u32 v[84:85], s[34:35], v120, s28, v[170:171]
	global_load_dwordx4 v[84:87], v[84:85], off
.LBB0_576:
	s_or_b64 exec, exec, s[58:59]
	s_and_b64 s[34:35], s[54:55], vcc
	v_mov_b32_e32 v156, 0
	v_mov_b32_e32 v164, 0
	v_mov_b32_e32 v165, 0
	v_mov_b32_e32 v166, 0
	v_mov_b32_e32 v167, 0
	s_and_saveexec_b64 s[58:59], s[34:35]
	v_mad_u64_u32 v[92:93], s[34:35], v92, s28, v[172:173]
	global_load_dwordx4 v[164:167], v[92:93], off
.LBB0_578:
	s_or_b64 exec, exec, s[58:59]
	s_and_b64 s[34:35], s[54:55], s[2:3]
	v_mov_b32_e32 v157, 0
	v_mov_b32_e32 v158, 0
	v_mov_b32_e32 v159, 0
	s_and_saveexec_b64 s[2:3], s[34:35]
	v_mad_u64_u32 v[92:93], s[34:35], v80, s28, v[172:173]
	global_load_dwordx4 v[156:159], v[92:93], off
.LBB0_580:
	s_or_b64 exec, exec, s[2:3]
	s_and_b64 s[4:5], s[54:55], s[4:5]
	v_mov_b32_e32 v112, 0
	v_mov_b32_e32 v160, 0
	v_mov_b32_e32 v161, 0
	v_mov_b32_e32 v162, 0
	v_mov_b32_e32 v163, 0
	s_and_saveexec_b64 s[2:3], s[4:5]
	v_mad_u64_u32 v[92:93], s[4:5], v81, s28, v[172:173]
	global_load_dwordx4 v[160:163], v[92:93], off
.LBB0_582:
	s_or_b64 exec, exec, s[2:3]
	s_and_b64 s[4:5], s[54:55], s[6:7]
	v_mov_b32_e32 v113, 0
	v_mov_b32_e32 v114, 0
	v_mov_b32_e32 v115, 0
	s_and_saveexec_b64 s[2:3], s[4:5]
	v_mad_u64_u32 v[92:93], s[4:5], v82, s28, v[172:173]
	global_load_dwordx4 v[112:115], v[92:93], off
.LBB0_584:
	s_or_b64 exec, exec, s[2:3]
	s_and_b64 s[4:5], s[54:55], s[8:9]
	v_mov_b32_e32 v92, 0
	v_mov_b32_e32 v116, 0
	v_mov_b32_e32 v117, 0
	v_mov_b32_e32 v118, 0
	v_mov_b32_e32 v119, 0
	s_and_saveexec_b64 s[2:3], s[4:5]
	v_mad_u64_u32 v[94:95], s[4:5], v83, s28, v[172:173]
	global_load_dwordx4 v[116:119], v[94:95], off

; __device__ __forceinline__ void phase_conv(PRef p, int layer, int nseg) {
;     ...
;         for (int hx = 0; hx < 2; ++hx) { const int xb = x0 + 4 * hx;
;             u32x4 gc[3][6], vv[4];
; #pragma unroll
;             for (int ky = 0; ky < 3; ++ky)
; #pragma unroll
;                 for (int cx = 0; cx < 6; ++cx) { const int xx = xb - 1 + cx;
;                     gc[ky][cx] = (lv[ky] && xx >= 0 && xx < W) ? *(const u32x4*)(lp[ky] + (size_t)xx * NUP) : (u32x4){0u, 0u, 0u, 0u}; }
.LBB0_1043:
	v_or_b32_e32 v90, s8, v226
	v_add_u32_e32 v48, -1, v90
	v_cmp_gt_u32_e32 vcc, 64, v48
	s_and_b64 s[46:47], s[38:39], vcc
	v_mov_b32_e32 v92, 0
	v_mul_lo_u32 v136, v48, s51
	v_mov_b32_e32 v96, 0
	v_mov_b32_e32 v97, 0
	v_mov_b32_e32 v98, 0
	v_mov_b32_e32 v99, 0
	s_and_saveexec_b64 s[8:9], s[46:47]
	v_lshl_add_u64 v[48:49], v[138:139], 0, v[136:137]
	global_load_dwordx4 v[96:99], v[48:49], off
.LBB0_1045:
	s_or_b64 exec, exec, s[8:9]
	v_mul_lo_u32 v48, v90, s51
	v_mov_b32_e32 v93, 0
	v_mov_b32_e32 v94, 0
	v_mov_b32_e32 v95, 0
	s_and_saveexec_b64 s[8:9], s[6:7]
	v_mov_b32_e32 v49, v137
	v_lshl_add_u64 v[50:51], v[138:139], 0, v[48:49]
	global_load_dwordx4 v[92:95], v[50:51], off
.LBB0_1047:
	s_or_b64 exec, exec, s[8:9]
	v_or_b32_e32 v91, 1, v90
	v_mov_b32_e32 v72, 0
	v_mul_lo_u32 v50, v91, s51
	v_mov_b32_e32 v100, 0
	v_mov_b32_e32 v101, 0
	v_mov_b32_e32 v102, 0
	v_mov_b32_e32 v103, 0
	s_and_saveexec_b64 s[8:9], s[6:7]
	v_mov_b32_e32 v51, v137
	v_lshl_add_u64 v[52:53], v[138:139], 0, v[50:51]
	global_load_dwordx4 v[100:103], v[52:53], off
.LBB0_1049:
	s_or_b64 exec, exec, s[8:9]
	v_or_b32_e32 v176, 2, v90
	v_mul_lo_u32 v60, v176, s51
	v_mov_b32_e32 v73, 0
	v_mov_b32_e32 v74, 0
	v_mov_b32_e32 v75, 0
	s_and_saveexec_b64 s[8:9], s[6:7]
	v_mov_b32_e32 v61, v137
	v_lshl_add_u64 v[52:53], v[138:139], 0, v[60:61]
	global_load_dwordx4 v[72:75], v[52:53], off
.LBB0_1051:
	s_or_b64 exec, exec, s[8:9]
	v_or_b32_e32 v177, 3, v90
	v_mov_b32_e32 v68, 0
	v_mul_lo_u32 v62, v177, s51
	v_mov_b32_e32 v76, 0
	v_mov_b32_e32 v77, 0
	v_mov_b32_e32 v78, 0
	v_mov_b32_e32 v79, 0
	s_and_saveexec_b64 s[8:9], s[6:7]
	v_mov_b32_e32 v63, v137
	v_lshl_add_u64 v[52:53], v[138:139], 0, v[62:63]
	global_load_dwordx4 v[76:79], v[52:53], off
.LBB0_1053:
	s_or_b64 exec, exec, s[8:9]
	v_add_u32_e32 v49, 4, v90
	v_cmp_gt_u32_e64 s[8:9], 64, v49
	s_and_b64 s[54:55], s[38:39], s[8:9]
	v_mul_lo_u32 v88, v49, s51
	v_mov_b32_e32 v69, 0
	v_mov_b32_e32 v70, 0
	v_mov_b32_e32 v71, 0
	s_and_saveexec_b64 s[46:47], s[54:55]
	v_mov_b32_e32 v89, v137
	v_lshl_add_u64 v[52:53], v[138:139], 0, v[88:89]
	global_load_dwordx4 v[68:71], v[52:53], off
.LBB0_1055:
	s_or_b64 exec, exec, s[46:47]
	v_mov_b32_e32 v116, 0
	v_mov_b32_e32 v112, 0
	v_mov_b32_e32 v113, 0
	v_mov_b32_e32 v114, 0
	v_mov_b32_e32 v115, 0
	s_and_saveexec_b64 s[46:47], vcc
	v_lshl_add_u64 v[52:53], v[140:141], 0, v[136:137]
	global_load_dwordx4 v[112:115], v[52:53], off
.LBB0_1057:
	s_or_b64 exec, exec, s[46:47]
	v_mov_b32_e32 v117, 0
	v_mov_b32_e32 v118, 0
	v_mov_b32_e32 v119, 0
	s_and_saveexec_b64 s[46:47], s[4:5]
	v_mov_b32_e32 v49, v137
	v_lshl_add_u64 v[52:53], v[140:141], 0, v[48:49]
	global_load_dwordx4 v[116:119], v[52:53], off
.LBB0_1059:
	s_or_b64 exec, exec, s[46:47]
	v_mov_b32_e32 v56, 0
	v_mov_b32_e32 v120, 0
	v_mov_b32_e32 v121, 0
	v_mov_b32_e32 v122, 0
	v_mov_b32_e32 v123, 0
	s_and_saveexec_b64 s[46:47], s[4:5]
	v_mov_b32_e32 v51, v137
	v_lshl_add_u64 v[52:53], v[140:141], 0, v[50:51]
	global_load_dwordx4 v[120:123], v[52:53], off
.LBB0_1061:
	s_or_b64 exec, exec, s[46:47]
	v_mov_b32_e32 v57, 0
	v_mov_b32_e32 v58, 0
	v_mov_b32_e32 v59, 0
	s_and_saveexec_b64 s[46:47], s[4:5]
	v_mov_b32_e32 v61, v137
	v_lshl_add_u64 v[52:53], v[140:141], 0, v[60:61]
	global_load_dwordx4 v[56:59], v[52:53], off
.LBB0_1063:
	s_or_b64 exec, exec, s[46:47]
	v_mov_b32_e32 v52, 0
	v_mov_b32_e32 v64, 0
	v_mov_b32_e32 v65, 0
	v_mov_b32_e32 v66, 0
	v_mov_b32_e32 v67, 0
	s_and_saveexec_b64 s[46:47], s[4:5]
	v_mov_b32_e32 v63, v137
	v_lshl_add_u64 v[54:55], v[140:141], 0, v[62:63]
	global_load_dwordx4 v[64:67], v[54:55], off
.LBB0_1065:
	s_or_b64 exec, exec, s[46:47]
	v_mov_b32_e32 v53, 0
	v_mov_b32_e32 v54, 0
	v_mov_b32_e32 v55, 0
	s_and_saveexec_b64 s[46:47], s[8:9]
	v_mov_b32_e32 v89, v137
	v_lshl_add_u64 v[52:53], v[140:141], 0, v[88:89]
	global_load_dwordx4 v[52:55], v[52:53], off
.LBB0_1067:
	s_or_b64 exec, exec, s[46:47]
	s_and_b64 s[54:55], s[40:41], vcc
	v_mov_b32_e32 v124, 0
	v_mov_b32_e32 v132, 0
	v_mov_b32_e32 v133, 0
	v_mov_b32_e32 v134, 0
	v_mov_b32_e32 v135, 0
	s_and_saveexec_b64 s[46:47], s[54:55]
	v_lshl_add_u64 v[80:81], v[142:143], 0, v[136:137]
	global_load_dwordx4 v[132:135], v[80:81], off
.LBB0_1069:
	s_or_b64 exec, exec, s[46:47]
	v_mov_b32_e32 v125, 0
	v_mov_b32_e32 v126, 0
	v_mov_b32_e32 v127, 0
	s_and_saveexec_b64 s[46:47], s[42:43]
	v_mov_b32_e32 v49, v137
	v_lshl_add_u64 v[48:49], v[142:143], 0, v[48:49]
	global_load_dwordx4 v[124:127], v[48:49], off
.LBB0_1071:
	s_or_b64 exec, exec, s[46:47]
	v_mov_b32_e32 v80, 0
	v_mov_b32_e32 v128, 0
	v_mov_b32_e32 v129, 0
	v_mov_b32_e32 v130, 0
	v_mov_b32_e32 v131, 0
	s_and_saveexec_b64 s[46:47], s[42:43]
	v_mov_b32_e32 v51, v137
	v_lshl_add_u64 v[48:49], v[142:143], 0, v[50:51]
	global_load_dwordx4 v[128:131], v[48:49], off
.LBB0_1073:
	s_or_b64 exec, exec, s[46:47]
	v_mov_b32_e32 v81, 0
	v_mov_b32_e32 v82, 0
	v_mov_b32_e32 v83, 0
	s_and_saveexec_b64 s[46:47], s[42:43]
	v_mov_b32_e32 v61, v137
	v_lshl_add_u64 v[48:49], v[142:143], 0, v[60:61]
	global_load_dwordx4 v[80:83], v[48:49], off
.LBB0_1075:
	s_or_b64 exec, exec, s[46:47]
	v_mov_b32_e32 v60, 0
	v_mov_b32_e32 v84, 0
	v_mov_b32_e32 v85, 0
	v_mov_b32_e32 v86, 0
	v_mov_b32_e32 v87, 0
	s_and_saveexec_b64 s[46:47], s[42:43]
	v_mov_b32_e32 v63, v137
	v_lshl_add_u64 v[48:49], v[142:143], 0, v[62:63]
	global_load_dwordx4 v[84:87], v[48:49], off
